# v120 + kernarg cache-line prefetch before each grid barrier (phase-top s_load hits instead of missing; in-kernel timing: 1.9us -> 0.9us per phase)
# speedup vs baseline: 1.0011x; 1.0011x over previous
.LBB0_458:
	s_nop 0
	v_readlane_b32 s0, v209, 42
	s_add_i32 s18, s0, 1
	s_load_dword s2, s[78:79], 0x0
	s_load_dword s3, s[78:79], 0x40
	s_load_dword s4, s[78:79], 0xa8
	v_readlane_b32 s0, v252, 0
	v_readlane_b32 s1, v252, 1
	s_cmp_ge_i32 s18, s0
	s_mov_b64 s[0:1], -1
	s_cbranch_scc0 .LBB0_459
	s_getpc_b64 s[98:99]
